# c36: window-attention bias table padded with the masked value so interior key tiles need no per-element index arithmetic or range checks (one immediate-offset lookup per element)
# speedup vs baseline: 1.0079x; 1.0036x over previous
; __device__ void attn_b_item(const Params& p, int item, int l, unsigned char* smem) {
;     ...
;     if (tid < 129) {
;         const int rel = tid - 64, n = (rel < 0 ? -rel : rel) * dil;
;         int bk;
;         if (n < 8) bk = n; else { bk = 8 + (n >= 15) + (n >= 27) + (n >= 50) + (n >= 91) + (n >= 166) + (n >= 305) + (n >= 559); }
;         if (rel > 0) bk += 16;
;         lut[tid] = p.rel_bias[bk * 12 + g * 4 + j] * LOG2E;
;     }
; #pragma unroll
;     for (int kt = 0; kt < 6; ++kt) { unsigned char* tb = smem + kt * ATB_TILE;
;         *(u32x4*)(tb + srow * 144 + sch * 16) = rk[kt]; *(u32x4*)(tb + 9216 + (sch >> 2) * 4096 + srow * 64 + (sch & 3) * 16) = rv[kt]; }
;     const int qpos = p0r + w * 32 + r32;
;     bf16x8 qr[4];
; #pragma unroll
;     for (int ds = 0; ds < 4; ++ds) qr[ds] = *(const bf16x8*)(QB + (size_t)qpos * 256 + ds * 16 + hi * 8);
;     const float nshift = -((const float*)(p.ws + WS_BND))[2 + l];
;     f32x16 o0, o1;
; #pragma unroll
;     for (int i = 0; i < 16; ++i) { o0[i] = 0.f; o1[i] = 0.f; }
;     f32x4 la4 = (f32x4){0.f, 0.f, 0.f, 0.f};
;     __syncthreads();
; #pragma unroll 1
;     for (int t3 = 0; t3 < 3; ++t3) {
;         const int kt = (w >> 1) + t3, kbase = p0r - 64 + 64 * kt;
;         const bf16_t* Ks = (const bf16_t*)(smem + kt * ATB_TILE); const unsigned char* Vs = smem + kt * ATB_TILE + 9216;
;         f32x16 p0, p1;
; #pragma unroll
;         for (int i = 0; i < 16; ++i) { p0[i] = nshift; p1[i] = nshift; }
.LBB0_785:
	s_or_b64 exec, exec, s[38:39]
	v_add_u32_e32 v52, 16, v51
	v_cmp_lt_i32_e32 vcc, 64, v48
	s_nop 1
	v_cndmask_b32_e32 v51, v51, v52, vcc
	v_mul_lo_u32 v51, v51, 12
	v_lshl_add_u32 v51, s18, 2, v51
	v_or_b32_e32 v52, s54, v51
	v_ashrrev_i32_e32 v53, 31, v52
	v_lshl_add_u64 v[52:53], v[52:53], 2, s[56:57]
	global_load_dword v51, v[52:53], off
	v_lshl_add_u32 v52, v48, 2, 0
	v_add_u32_e32 v52, 0x19d00, v52
	s_waitcnt vmcnt(0)
	v_mul_f32_e32 v51, 0x3fb8aa3b, v51
	ds_write_b32 v52, v51
.LBB0_786:
	s_or_b64 exec, exec, s[36:37]
	v_mov_b32_e32 v148, 0xc4800000
	v_and_b32_e32 v149, 63, v210
	v_lshlrev_b32_e32 v149, 2, v149
	v_add_u32_e32 v149, 0x19c00, v149
	ds_write_b32 v149, v148
	ds_write_b32 v149, v148 offset:772
	s_lshr_b32 s22, 0x2000, s16
	s_sub_i32 s16, 13, s16
	s_lshl_b64 s[36:37], s[42:43], 21
	s_ashr_i32 s58, s17, 1
	v_mul_lo_u32 v52, v49, s3
	s_lshr_b32 s59, s9, s16
	v_readlane_b32 s16, v255, 4
	s_lshl_b32 s18, s54, 6
	s_and_b32 s19, s52, 0x1f00
	s_lshl_b64 s[20:21], s[36:37], 1
	v_lshlrev_b32_e32 v50, 10, v50
	s_andn2_b32 s58, s58, 31
	v_add3_u32 v57, s16, v52, v80
	v_readlane_b32 s16, v255, 6
	v_and_b32_e32 v50, 0x1000, v50
	v_add3_u32 v56, 0, v52, v80
	v_add3_u32 v52, s16, v52, v80
	s_add_u32 s16, s48, s20
	v_readlane_b32 s20, v255, 5
	s_waitcnt vmcnt(11)
	ds_write_b128 v56, v[36:39]
	v_and_b32_e32 v137, 31, v48
	v_add_u32_e32 v37, s20, v50
	v_readlane_b32 s20, v255, 7
	v_lshlrev_b32_e32 v53, 4, v48
	v_lshlrev_b32_e32 v49, 6, v49
	v_add_u32_e32 v38, s20, v50
	s_addc_u32 s20, s49, s21
	s_lshl_b32 s18, s18, 1
	s_add_u32 s44, s16, s18
	s_addc_u32 s45, s20, 0
	s_add_i32 s55, s58, s9
	v_and_b32_e32 v55, 48, v53
	v_add_u32_e32 v36, 0, v50
	v_or_b32_e32 v130, s55, v137
	v_add3_u32 v36, v36, v49, v55
	v_ashrrev_i32_e32 v131, 31, v130
	global_load_dword v138, v81, s[40:41]
	v_bfe_u32 v51, v48, 5, 1
	s_waitcnt vmcnt(11)
	ds_write_b128 v36, v[20:23] offset:9216
	s_waitcnt vmcnt(10)
	ds_write_b128 v56, v[32:35] offset:17408
	v_lshlrev_b64 v[20:21], 9, v[130:131]
	v_lshlrev_b32_e32 v80, 4, v51
	v_lshl_add_u64 v[20:21], s[44:45], 0, v[20:21]
	v_lshl_add_u64 v[20:21], v[20:21], 0, v[80:81]
	global_load_dwordx4 v[82:85], v[20:21], off
	global_load_dwordx4 v[86:89], v[20:21], off offset:32
	global_load_dwordx4 v[90:93], v[20:21], off offset:64
	global_load_dwordx4 v[94:97], v[20:21], off offset:96
	s_ashr_i32 s61, s17, 7
	v_lshlrev_b32_e32 v136, 2, v51
	s_lshl_b32 s9, s61, 6
	v_add3_u32 v37, v37, v49, v55
	v_add3_u32 v38, v38, v49, v55
	s_waitcnt vmcnt(13)
	ds_write_b128 v36, v[8:11] offset:26624
	s_waitcnt vmcnt(12)
	ds_write_b128 v56, v[0:3] offset:34816
	s_waitcnt vmcnt(11)
	ds_write_b128 v36, v[4:7] offset:44032
	s_waitcnt vmcnt(10)
	ds_write_b128 v56, v[12:15] offset:52224
	s_waitcnt vmcnt(9)
	ds_write_b128 v36, v[16:19] offset:61440
	s_waitcnt vmcnt(8)
	ds_write_b128 v57, v[24:27]
	s_waitcnt vmcnt(7)
	ds_write_b128 v37, v[28:31]
	s_waitcnt vmcnt(6)
	ds_write_b128 v52, v[40:43]
	s_waitcnt vmcnt(5)
	ds_write_b128 v38, v[44:47]
	v_or_b32_e32 v0, s9, v136
	v_sub_u32_e32 v0, v0, v137
	v_and_b32_e32 v139, 63, v48
	v_lshlrev_b32_e32 v54, 1, v48
	v_lshlrev_b32_e32 v48, 3, v48
	s_add_i32 s19, s19, s9
	v_subrev_u32_e32 v141, s58, v0
	v_and_b32_e32 v0, 0xc0, v53
	s_movk_i32 s9, 0x100
	v_and_b32_e32 v54, 32, v54
	v_and_b32_e32 v59, 24, v48
	v_and_or_b32 v0, v48, s9, v0
	v_mul_u32_u24_e32 v58, 0x90, v137
	s_mul_i32 s59, s59, s22
	v_or3_b32 v0, v0, v54, v59
	v_mov_b32_e32 v132, 0
	s_add_i32 s60, s59, s22
	v_or_b32_e32 v140, s19, v136
	s_mulk_i32 s61, 0x4400
	v_add_u32_e32 v142, 0, v0
	v_add3_u32 v80, v58, v80, 0
	s_mov_b32 s62, 0
	v_mov_b32_e32 v133, v132
	v_mov_b32_e32 v134, v132
	v_mov_b32_e32 v135, v132
	v_mov_b32_e32 v0, v132
	v_mov_b32_e32 v1, v132
	v_mov_b32_e32 v2, v132
	v_mov_b32_e32 v3, v132
	v_mov_b32_e32 v4, v132
	v_mov_b32_e32 v5, v132
	v_mov_b32_e32 v6, v132
	v_mov_b32_e32 v7, v132
	v_mov_b32_e32 v8, v132
	v_mov_b32_e32 v9, v132
	v_mov_b32_e32 v10, v132
	v_mov_b32_e32 v11, v132
	v_mov_b32_e32 v12, v132
	v_mov_b32_e32 v13, v132
	v_mov_b32_e32 v14, v132
	v_mov_b32_e32 v15, v132
	v_mov_b32_e32 v16, v132
	v_mov_b32_e32 v17, v132
	v_mov_b32_e32 v18, v132
	v_mov_b32_e32 v19, v132
	v_mov_b32_e32 v20, v132
	v_mov_b32_e32 v21, v132
	v_mov_b32_e32 v22, v132
	v_mov_b32_e32 v23, v132
	v_mov_b32_e32 v24, v132
	v_mov_b32_e32 v25, v132
	v_mov_b32_e32 v26, v132
	v_mov_b32_e32 v27, v132
	v_mov_b32_e32 v28, v132
	v_mov_b32_e32 v29, v132
	v_mov_b32_e32 v30, v132
	v_mov_b32_e32 v31, v132
	s_waitcnt lgkmcnt(0)
	s_barrier
	s_waitcnt vmcnt(4)
	v_xor_b32_e32 v32, 0x80000000, v138
	v_mov_b32_e32 v33, v32
	v_mov_b32_e32 v34, v32
	v_mov_b32_e32 v35, v32
	v_mov_b32_e32 v36, v32
	v_mov_b32_e32 v37, v32
	v_mov_b32_e32 v38, v32
	v_mov_b32_e32 v39, v32
	v_mov_b32_e32 v40, v32
	v_mov_b32_e32 v41, v32
	v_mov_b32_e32 v42, v32
	v_mov_b32_e32 v43, v32
	v_mov_b32_e32 v44, v32
	v_mov_b32_e32 v45, v32
	v_mov_b32_e32 v46, v32
	v_mov_b32_e32 v47, v32
; __device__ __forceinline__ int crow(int r, int hi) { return (r & 3) + 8 * (r >> 2) + 4 * hi; }
; __device__ void attn_b_item(const Params& p, int item, int l, unsigned char* smem) {
;     ...
;     for (int t3 = 0; t3 < 3; ++t3) {
;         const int kt = (w >> 1) + t3, kbase = p0r - 64 + 64 * kt;
;         const bf16_t* Ks = (const bf16_t*)(smem + kt * ATB_TILE); const unsigned char* Vs = smem + kt * ATB_TILE + 9216;
;         f32x16 p0, p1;
; #pragma unroll
;         for (int i = 0; i < 16; ++i) { p0[i] = nshift; p1[i] = nshift; }
;         at_qk(p0, p1, Ks, qr, r32, hi);
;         bf16x8 vf0[4], vf1[4];
;         at_ldv(vf0, vf1, Vs, lane); __builtin_amdgcn_sched_barrier(0);
; #pragma unroll
;         for (int i = 0; i < 16; ++i) {
;             const int kv0 = kbase + crow(i, hi), kv1 = kv0 + 32;
;             const int rel0 = kv0 - qpos, rel1 = kv1 - qpos;
;             const bool ok0 = rel0 >= -64 && rel0 <= 64 && kv0 >= seq_lo && kv0 < seq_hi;
;             const bool ok1 = rel1 >= -64 && rel1 <= 64 && kv1 >= seq_lo && kv1 < seq_hi;
;             const float e0 = __builtin_amdgcn_exp2f(p0[i] + lut[ok0 ? rel0 + 64 : 64]);
;             const float e1 = __builtin_amdgcn_exp2f(p1[i] + lut[ok1 ? rel1 + 64 : 64]);
;             p0[i] = ok0 ? e0 : 0.f; p1[i] = ok1 ? e1 : 0.f;
;         }
.LBB0_787:
	v_add_u32_e32 v52, s61, v80
	ds_read_b128 v[48:51], v52
	ds_read_b128 v[98:101], v52 offset:32
	ds_read_b128 v[102:105], v52 offset:4608
	ds_read_b128 v[106:109], v52 offset:4640
	ds_read_b128 v[110:113], v52 offset:64
	ds_read_b128 v[114:117], v52 offset:96
	ds_read_b128 v[118:121], v52 offset:4672
	ds_read_b128 v[122:125], v52 offset:4704
	s_setprio 1
	s_waitcnt vmcnt(3) lgkmcnt(7)
	v_mfma_f32_32x32x16_bf16 v[64:79], v[48:51], v[82:85], v[32:47]
	s_waitcnt lgkmcnt(5)
	v_mfma_f32_32x32x16_bf16 v[48:63], v[102:105], v[82:85], v[32:47]
	s_waitcnt vmcnt(2)
	v_mfma_f32_32x32x16_bf16 v[64:79], v[98:101], v[86:89], v[64:79]
	s_waitcnt lgkmcnt(4)
	v_mfma_f32_32x32x16_bf16 v[48:63], v[106:109], v[86:89], v[48:63]
	s_waitcnt vmcnt(1) lgkmcnt(3)
	v_mfma_f32_32x32x16_bf16 v[64:79], v[110:113], v[90:93], v[64:79]
	s_waitcnt lgkmcnt(1)
	v_mfma_f32_32x32x16_bf16 v[48:63], v[118:121], v[90:93], v[48:63]
	s_waitcnt vmcnt(0)
	v_mfma_f32_32x32x16_bf16 v[64:79], v[114:117], v[94:97], v[64:79]
	s_waitcnt lgkmcnt(0)
	v_mfma_f32_32x32x16_bf16 v[48:63], v[122:125], v[94:97], v[48:63]
	s_setprio 0
	v_add_u32_e32 v104, s61, v142
	ds_read_b64_tr_b16 v[122:123], v104 offset:9216
	ds_read_b64_tr_b16 v[124:125], v104 offset:9728
	ds_read_b64_tr_b16 v[110:111], v104 offset:10240
	ds_read_b64_tr_b16 v[112:113], v104 offset:10752
	ds_read_b64_tr_b16 v[126:127], v104 offset:13312
	ds_read_b64_tr_b16 v[128:129], v104 offset:13824
	ds_read_b64_tr_b16 v[118:119], v104 offset:14336
	ds_read_b64_tr_b16 v[120:121], v104 offset:14848
	ds_read_b64_tr_b16 v[106:107], v104 offset:11264
	ds_read_b64_tr_b16 v[108:109], v104 offset:11776
	ds_read_b64_tr_b16 v[98:99], v104 offset:12288
	ds_read_b64_tr_b16 v[100:101], v104 offset:12800
	ds_read_b64_tr_b16 v[114:115], v104 offset:15360
	ds_read_b64_tr_b16 v[116:117], v104 offset:15872
	ds_read_b64_tr_b16 v[102:103], v104 offset:16384
	ds_read_b64_tr_b16 v[104:105], v104 offset:16896
	s_add_i32 s9, 0, 0x19d00
	v_add_u32_e32 v144, s62, v140
	v_add_u32_e32 v143, s62, v141
	s_sub_i32 s99, s60, s59
	v_mov_b32_e32 v184, 0x81
	v_subrev_u32_e32 v180, s59, v144
	v_subrev_u32_e32 v180, 64, v180
	v_readfirstlane_b32 s100, v140
	s_add_i32 s100, s100, s62
	s_sub_i32 s100, s100, s59
	s_sub_i32 s100, s100, 64
	s_sub_i32 s101, s99, 63
	s_waitcnt lgkmcnt(0)
	s_cmp_lt_u32 s100, s101
	s_cbranch_scc1 .Latb_fast
	v_add_u32_e32 v148, 0, v143
	v_add_u32_e32 v182, 0, v180
	v_add_u32_e32 v149, 32, v143
	v_add_u32_e32 v183, 32, v180
	v_cmp_gt_u32_e32 vcc, s4, v148
	v_cmp_gt_u32_e64 s[36:37], s99, v182
	v_cmp_gt_u32_e64 s[38:39], s4, v149
	v_cmp_gt_u32_e64 s[16:17], s99, v183
	s_and_b64 vcc, vcc, s[36:37]
	s_and_b64 s[38:39], s[38:39], s[16:17]
	v_cndmask_b32_e32 v148, v184, v148, vcc
	v_cndmask_b32_e64 v149, v184, v149, s[38:39]
	v_lshl_add_u32 v148, v148, 2, s9
	v_lshl_add_u32 v149, v149, 2, s9
	ds_read_b32 v148, v148
	ds_read_b32 v149, v149
	v_add_u32_e32 v150, 1, v143
	v_add_u32_e32 v182, 1, v180
	v_add_u32_e32 v151, 33, v143
	v_add_u32_e32 v183, 33, v180
	v_cmp_gt_u32_e32 vcc, s4, v150
	v_cmp_gt_u32_e64 s[36:37], s99, v182
	v_cmp_gt_u32_e64 s[38:39], s4, v151
	v_cmp_gt_u32_e64 s[16:17], s99, v183
	s_and_b64 vcc, vcc, s[36:37]
	s_and_b64 s[38:39], s[38:39], s[16:17]
	v_cndmask_b32_e32 v150, v184, v150, vcc
	v_cndmask_b32_e64 v151, v184, v151, s[38:39]
	v_lshl_add_u32 v150, v150, 2, s9
	v_lshl_add_u32 v151, v151, 2, s9
	ds_read_b32 v150, v150
	ds_read_b32 v151, v151
	v_add_u32_e32 v152, 2, v143
	v_add_u32_e32 v182, 2, v180
	v_add_u32_e32 v153, 34, v143
	v_add_u32_e32 v183, 34, v180
	v_cmp_gt_u32_e32 vcc, s4, v152
	v_cmp_gt_u32_e64 s[36:37], s99, v182
	v_cmp_gt_u32_e64 s[38:39], s4, v153
	v_cmp_gt_u32_e64 s[16:17], s99, v183
	s_and_b64 vcc, vcc, s[36:37]
	s_and_b64 s[38:39], s[38:39], s[16:17]
	v_cndmask_b32_e32 v152, v184, v152, vcc
	v_cndmask_b32_e64 v153, v184, v153, s[38:39]
	v_lshl_add_u32 v152, v152, 2, s9
	v_lshl_add_u32 v153, v153, 2, s9
	ds_read_b32 v152, v152
	ds_read_b32 v153, v153
	v_add_u32_e32 v154, 3, v143
	v_add_u32_e32 v182, 3, v180
	v_add_u32_e32 v155, 35, v143
	v_add_u32_e32 v183, 35, v180
	v_cmp_gt_u32_e32 vcc, s4, v154
	v_cmp_gt_u32_e64 s[36:37], s99, v182
	v_cmp_gt_u32_e64 s[38:39], s4, v155
	v_cmp_gt_u32_e64 s[16:17], s99, v183
	s_and_b64 vcc, vcc, s[36:37]
	s_and_b64 s[38:39], s[38:39], s[16:17]
	v_cndmask_b32_e32 v154, v184, v154, vcc
	v_cndmask_b32_e64 v155, v184, v155, s[38:39]
	v_lshl_add_u32 v154, v154, 2, s9
	v_lshl_add_u32 v155, v155, 2, s9
	ds_read_b32 v154, v154
	ds_read_b32 v155, v155
	s_waitcnt lgkmcnt(6)
	v_add_f32_e32 v64, v64, v148
	v_add_f32_e32 v48, v48, v149
	v_exp_f32_e32 v181, v64
	v_exp_f32_e32 v64, v48
	v_mov_b32_e32 v48, v181
	s_waitcnt lgkmcnt(4)
	v_add_f32_e32 v65, v65, v150
	v_add_f32_e32 v49, v49, v151
	v_exp_f32_e32 v181, v65
	v_exp_f32_e32 v65, v49
	v_mov_b32_e32 v49, v181
	s_waitcnt lgkmcnt(2)
	v_add_f32_e32 v66, v66, v152
	v_add_f32_e32 v50, v50, v153
	v_exp_f32_e32 v181, v66
	v_exp_f32_e32 v66, v50
	v_mov_b32_e32 v50, v181
	s_waitcnt lgkmcnt(0)
; __device__ __forceinline__ int crow(int r, int hi) { return (r & 3) + 8 * (r >> 2) + 4 * hi; }
; __device__ void attn_b_item(const Params& p, int item, int l, unsigned char* smem) {
;     ...
;         for (int i = 0; i < 16; ++i) {
;             const int kv0 = kbase + crow(i, hi), kv1 = kv0 + 32;
;             const int rel0 = kv0 - qpos, rel1 = kv1 - qpos;
;             const bool ok0 = rel0 >= -64 && rel0 <= 64 && kv0 >= seq_lo && kv0 < seq_hi;
;             const bool ok1 = rel1 >= -64 && rel1 <= 64 && kv1 >= seq_lo && kv1 < seq_hi;
;             const float e0 = __builtin_amdgcn_exp2f(p0[i] + lut[ok0 ? rel0 + 64 : 64]);
;             const float e1 = __builtin_amdgcn_exp2f(p1[i] + lut[ok1 ? rel1 + 64 : 64]);
;             p0[i] = ok0 ? e0 : 0.f; p1[i] = ok1 ? e1 : 0.f;
;         }
	v_add_f32_e32 v67, v67, v154
	v_add_f32_e32 v51, v51, v155
	v_exp_f32_e32 v181, v67
	v_exp_f32_e32 v67, v51
	v_mov_b32_e32 v51, v181
	v_add_u32_e32 v156, 8, v143
	v_add_u32_e32 v182, 8, v180
	v_add_u32_e32 v157, 40, v143
	v_add_u32_e32 v183, 40, v180
	v_cmp_gt_u32_e32 vcc, s4, v156
	v_cmp_gt_u32_e64 s[36:37], s99, v182
	v_cmp_gt_u32_e64 s[38:39], s4, v157
	v_cmp_gt_u32_e64 s[16:17], s99, v183
	s_and_b64 vcc, vcc, s[36:37]
	s_and_b64 s[38:39], s[38:39], s[16:17]
	v_cndmask_b32_e32 v156, v184, v156, vcc
	v_cndmask_b32_e64 v157, v184, v157, s[38:39]
	v_lshl_add_u32 v156, v156, 2, s9
	v_lshl_add_u32 v157, v157, 2, s9
	ds_read_b32 v156, v156
	ds_read_b32 v157, v157
	v_add_u32_e32 v158, 9, v143
	v_add_u32_e32 v182, 9, v180
	v_add_u32_e32 v159, 41, v143
	v_add_u32_e32 v183, 41, v180
	v_cmp_gt_u32_e32 vcc, s4, v158
	v_cmp_gt_u32_e64 s[36:37], s99, v182
	v_cmp_gt_u32_e64 s[38:39], s4, v159
	v_cmp_gt_u32_e64 s[16:17], s99, v183
	s_and_b64 vcc, vcc, s[36:37]
	s_and_b64 s[38:39], s[38:39], s[16:17]
	v_cndmask_b32_e32 v158, v184, v158, vcc
	v_cndmask_b32_e64 v159, v184, v159, s[38:39]
	v_lshl_add_u32 v158, v158, 2, s9
	v_lshl_add_u32 v159, v159, 2, s9
	ds_read_b32 v158, v158
	ds_read_b32 v159, v159
	v_add_u32_e32 v160, 10, v143
	v_add_u32_e32 v182, 10, v180
	v_add_u32_e32 v161, 42, v143
	v_add_u32_e32 v183, 42, v180
	v_cmp_gt_u32_e32 vcc, s4, v160
	v_cmp_gt_u32_e64 s[36:37], s99, v182
	v_cmp_gt_u32_e64 s[38:39], s4, v161
	v_cmp_gt_u32_e64 s[16:17], s99, v183
	s_and_b64 vcc, vcc, s[36:37]
	s_and_b64 s[38:39], s[38:39], s[16:17]
	v_cndmask_b32_e32 v160, v184, v160, vcc
	v_cndmask_b32_e64 v161, v184, v161, s[38:39]
	v_lshl_add_u32 v160, v160, 2, s9
	v_lshl_add_u32 v161, v161, 2, s9
	ds_read_b32 v160, v160
	ds_read_b32 v161, v161
	v_add_u32_e32 v162, 11, v143
	v_add_u32_e32 v182, 11, v180
	v_add_u32_e32 v163, 43, v143
	v_add_u32_e32 v183, 43, v180
	v_cmp_gt_u32_e32 vcc, s4, v162
	v_cmp_gt_u32_e64 s[36:37], s99, v182
	v_cmp_gt_u32_e64 s[38:39], s4, v163
	v_cmp_gt_u32_e64 s[16:17], s99, v183
	s_and_b64 vcc, vcc, s[36:37]
	s_and_b64 s[38:39], s[38:39], s[16:17]
	v_cndmask_b32_e32 v162, v184, v162, vcc
	v_cndmask_b32_e64 v163, v184, v163, s[38:39]
	v_lshl_add_u32 v162, v162, 2, s9
	v_lshl_add_u32 v163, v163, 2, s9
	ds_read_b32 v162, v162
	ds_read_b32 v163, v163
	s_waitcnt lgkmcnt(6)
	v_add_f32_e32 v68, v68, v156
	v_add_f32_e32 v52, v52, v157
	v_exp_f32_e32 v181, v68
	v_exp_f32_e32 v68, v52
	v_mov_b32_e32 v52, v181
	s_waitcnt lgkmcnt(4)
	v_add_f32_e32 v69, v69, v158
	v_add_f32_e32 v53, v53, v159
	v_exp_f32_e32 v181, v69
	v_exp_f32_e32 v69, v53
	v_mov_b32_e32 v53, v181
	s_waitcnt lgkmcnt(2)
	v_add_f32_e32 v70, v70, v160
	v_add_f32_e32 v54, v54, v161
	v_exp_f32_e32 v181, v70
	v_exp_f32_e32 v70, v54
	v_mov_b32_e32 v54, v181
	s_waitcnt lgkmcnt(0)
	v_add_f32_e32 v71, v71, v162
	v_add_f32_e32 v55, v55, v163
	v_exp_f32_e32 v181, v71
	v_exp_f32_e32 v71, v55
	v_mov_b32_e32 v55, v181
	v_add_u32_e32 v164, 16, v143
	v_add_u32_e32 v182, 16, v180
	v_add_u32_e32 v165, 48, v143
	v_add_u32_e32 v183, 48, v180
	v_cmp_gt_u32_e32 vcc, s4, v164
	v_cmp_gt_u32_e64 s[36:37], s99, v182
	v_cmp_gt_u32_e64 s[38:39], s4, v165
	v_cmp_gt_u32_e64 s[16:17], s99, v183
	s_and_b64 vcc, vcc, s[36:37]
	s_and_b64 s[38:39], s[38:39], s[16:17]
	v_cndmask_b32_e32 v164, v184, v164, vcc
	v_cndmask_b32_e64 v165, v184, v165, s[38:39]
	v_lshl_add_u32 v164, v164, 2, s9
	v_lshl_add_u32 v165, v165, 2, s9
	ds_read_b32 v164, v164
	ds_read_b32 v165, v165
	v_add_u32_e32 v166, 17, v143
	v_add_u32_e32 v182, 17, v180
	v_add_u32_e32 v167, 49, v143
	v_add_u32_e32 v183, 49, v180
	v_cmp_gt_u32_e32 vcc, s4, v166
	v_cmp_gt_u32_e64 s[36:37], s99, v182
	v_cmp_gt_u32_e64 s[38:39], s4, v167
	v_cmp_gt_u32_e64 s[16:17], s99, v183
	s_and_b64 vcc, vcc, s[36:37]
	s_and_b64 s[38:39], s[38:39], s[16:17]
	v_cndmask_b32_e32 v166, v184, v166, vcc
	v_cndmask_b32_e64 v167, v184, v167, s[38:39]
	v_lshl_add_u32 v166, v166, 2, s9
	v_lshl_add_u32 v167, v167, 2, s9
	ds_read_b32 v166, v166
	ds_read_b32 v167, v167
	v_add_u32_e32 v168, 18, v143
	v_add_u32_e32 v182, 18, v180
	v_add_u32_e32 v169, 50, v143
	v_add_u32_e32 v183, 50, v180
	v_cmp_gt_u32_e32 vcc, s4, v168
	v_cmp_gt_u32_e64 s[36:37], s99, v182
	v_cmp_gt_u32_e64 s[38:39], s4, v169
	v_cmp_gt_u32_e64 s[16:17], s99, v183
	s_and_b64 vcc, vcc, s[36:37]
	s_and_b64 s[38:39], s[38:39], s[16:17]
	v_cndmask_b32_e32 v168, v184, v168, vcc
	v_cndmask_b32_e64 v169, v184, v169, s[38:39]
	v_lshl_add_u32 v168, v168, 2, s9
	v_lshl_add_u32 v169, v169, 2, s9
	ds_read_b32 v168, v168
	ds_read_b32 v169, v169
	v_add_u32_e32 v170, 19, v143
	v_add_u32_e32 v182, 19, v180
	v_add_u32_e32 v171, 51, v143
	v_add_u32_e32 v183, 51, v180
	v_cmp_gt_u32_e32 vcc, s4, v170
	v_cmp_gt_u32_e64 s[36:37], s99, v182
	v_cmp_gt_u32_e64 s[38:39], s4, v171
	v_cmp_gt_u32_e64 s[16:17], s99, v183
	s_and_b64 vcc, vcc, s[36:37]
	s_and_b64 s[38:39], s[38:39], s[16:17]
	v_cndmask_b32_e32 v170, v184, v170, vcc
	v_cndmask_b32_e64 v171, v184, v171, s[38:39]
	v_lshl_add_u32 v170, v170, 2, s9
	v_lshl_add_u32 v171, v171, 2, s9
	ds_read_b32 v170, v170
	ds_read_b32 v171, v171
	s_waitcnt lgkmcnt(6)
	v_add_f32_e32 v72, v72, v164
	v_add_f32_e32 v56, v56, v165
	v_exp_f32_e32 v181, v72
	v_exp_f32_e32 v72, v56
	v_mov_b32_e32 v56, v181
	s_waitcnt lgkmcnt(4)
	v_add_f32_e32 v73, v73, v166
	v_add_f32_e32 v57, v57, v167
	v_exp_f32_e32 v181, v73
	v_exp_f32_e32 v73, v57
	v_mov_b32_e32 v57, v181
	s_waitcnt lgkmcnt(2)
	v_add_f32_e32 v74, v74, v168
	v_add_f32_e32 v58, v58, v169
	v_exp_f32_e32 v181, v74
	v_exp_f32_e32 v74, v58
	v_mov_b32_e32 v58, v181
	s_waitcnt lgkmcnt(0)
; __device__ __forceinline__ int crow(int r, int hi) { return (r & 3) + 8 * (r >> 2) + 4 * hi; }
; __device__ void attn_b_item(const Params& p, int item, int l, unsigned char* smem) {
;     ...
;         for (int i = 0; i < 16; ++i) {
;             const int kv0 = kbase + crow(i, hi), kv1 = kv0 + 32;
;             const int rel0 = kv0 - qpos, rel1 = kv1 - qpos;
;             const bool ok0 = rel0 >= -64 && rel0 <= 64 && kv0 >= seq_lo && kv0 < seq_hi;
;             const bool ok1 = rel1 >= -64 && rel1 <= 64 && kv1 >= seq_lo && kv1 < seq_hi;
;             const float e0 = __builtin_amdgcn_exp2f(p0[i] + lut[ok0 ? rel0 + 64 : 64]);
;             const float e1 = __builtin_amdgcn_exp2f(p1[i] + lut[ok1 ? rel1 + 64 : 64]);
;             p0[i] = ok0 ? e0 : 0.f; p1[i] = ok1 ? e1 : 0.f;
;         }
	v_add_f32_e32 v75, v75, v170
	v_add_f32_e32 v59, v59, v171
	v_exp_f32_e32 v181, v75
	v_exp_f32_e32 v75, v59
	v_mov_b32_e32 v59, v181
	v_add_u32_e32 v172, 24, v143
	v_add_u32_e32 v182, 24, v180
	v_add_u32_e32 v173, 56, v143
	v_add_u32_e32 v183, 56, v180
	v_cmp_gt_u32_e32 vcc, s4, v172
	v_cmp_gt_u32_e64 s[36:37], s99, v182
	v_cmp_gt_u32_e64 s[38:39], s4, v173
	v_cmp_gt_u32_e64 s[16:17], s99, v183
	s_and_b64 vcc, vcc, s[36:37]
	s_and_b64 s[38:39], s[38:39], s[16:17]
	v_cndmask_b32_e32 v172, v184, v172, vcc
	v_cndmask_b32_e64 v173, v184, v173, s[38:39]
	v_lshl_add_u32 v172, v172, 2, s9
	v_lshl_add_u32 v173, v173, 2, s9
	ds_read_b32 v172, v172
	ds_read_b32 v173, v173
	v_add_u32_e32 v174, 25, v143
	v_add_u32_e32 v182, 25, v180
	v_add_u32_e32 v175, 57, v143
	v_add_u32_e32 v183, 57, v180
	v_cmp_gt_u32_e32 vcc, s4, v174
	v_cmp_gt_u32_e64 s[36:37], s99, v182
	v_cmp_gt_u32_e64 s[38:39], s4, v175
	v_cmp_gt_u32_e64 s[16:17], s99, v183
	s_and_b64 vcc, vcc, s[36:37]
	s_and_b64 s[38:39], s[38:39], s[16:17]
	v_cndmask_b32_e32 v174, v184, v174, vcc
	v_cndmask_b32_e64 v175, v184, v175, s[38:39]
	v_lshl_add_u32 v174, v174, 2, s9
	v_lshl_add_u32 v175, v175, 2, s9
	ds_read_b32 v174, v174
	ds_read_b32 v175, v175
	v_add_u32_e32 v176, 26, v143
	v_add_u32_e32 v182, 26, v180
	v_add_u32_e32 v177, 58, v143
	v_add_u32_e32 v183, 58, v180
	v_cmp_gt_u32_e32 vcc, s4, v176
	v_cmp_gt_u32_e64 s[36:37], s99, v182
	v_cmp_gt_u32_e64 s[38:39], s4, v177
	v_cmp_gt_u32_e64 s[16:17], s99, v183
	s_and_b64 vcc, vcc, s[36:37]
	s_and_b64 s[38:39], s[38:39], s[16:17]
	v_cndmask_b32_e32 v176, v184, v176, vcc
	v_cndmask_b32_e64 v177, v184, v177, s[38:39]
	v_lshl_add_u32 v176, v176, 2, s9
	v_lshl_add_u32 v177, v177, 2, s9
	ds_read_b32 v176, v176
	ds_read_b32 v177, v177
	v_add_u32_e32 v178, 27, v143
	v_add_u32_e32 v182, 27, v180
	v_add_u32_e32 v179, 59, v143
	v_add_u32_e32 v183, 59, v180
	v_cmp_gt_u32_e32 vcc, s4, v178
	v_cmp_gt_u32_e64 s[36:37], s99, v182
	v_cmp_gt_u32_e64 s[38:39], s4, v179
	v_cmp_gt_u32_e64 s[16:17], s99, v183
	s_and_b64 vcc, vcc, s[36:37]
	s_and_b64 s[38:39], s[38:39], s[16:17]
	v_cndmask_b32_e32 v178, v184, v178, vcc
	v_cndmask_b32_e64 v179, v184, v179, s[38:39]
	v_lshl_add_u32 v178, v178, 2, s9
	v_lshl_add_u32 v179, v179, 2, s9
	ds_read_b32 v178, v178
	ds_read_b32 v179, v179
	s_waitcnt lgkmcnt(6)
	v_add_f32_e32 v76, v76, v172
	v_add_f32_e32 v60, v60, v173
	v_exp_f32_e32 v181, v76
	v_exp_f32_e32 v76, v60
	v_mov_b32_e32 v60, v181
	s_waitcnt lgkmcnt(4)
	v_add_f32_e32 v77, v77, v174
	v_add_f32_e32 v61, v61, v175
	v_exp_f32_e32 v181, v77
	v_exp_f32_e32 v77, v61
	v_mov_b32_e32 v61, v181
	s_waitcnt lgkmcnt(2)
	v_add_f32_e32 v78, v78, v176
	v_add_f32_e32 v62, v62, v177
	v_exp_f32_e32 v181, v78
	v_exp_f32_e32 v78, v62
	v_mov_b32_e32 v62, v181
	s_waitcnt lgkmcnt(0)
	v_add_f32_e32 v79, v79, v178
	v_add_f32_e32 v63, v63, v179
	v_exp_f32_e32 v181, v79
	v_exp_f32_e32 v79, v63
	v_mov_b32_e32 v63, v181
	s_branch .Latb_join
.Latb_fast:
	v_lshl_add_u32 v182, v143, 2, s9
	ds_read_b32 v148, v182
	ds_read_b32 v149, v182 offset:128
	ds_read_b32 v150, v182 offset:4
	ds_read_b32 v151, v182 offset:132
	ds_read_b32 v152, v182 offset:8
	ds_read_b32 v153, v182 offset:136
	ds_read_b32 v154, v182 offset:12
	ds_read_b32 v155, v182 offset:140
	s_waitcnt lgkmcnt(6)
	v_add_f32_e32 v64, v64, v148
	v_add_f32_e32 v48, v48, v149
	v_exp_f32_e32 v181, v64
	v_exp_f32_e32 v64, v48
	v_mov_b32_e32 v48, v181
	s_waitcnt lgkmcnt(4)
	v_add_f32_e32 v65, v65, v150
	v_add_f32_e32 v49, v49, v151
	v_exp_f32_e32 v181, v65
	v_exp_f32_e32 v65, v49
	v_mov_b32_e32 v49, v181
	s_waitcnt lgkmcnt(2)
	v_add_f32_e32 v66, v66, v152
	v_add_f32_e32 v50, v50, v153
	v_exp_f32_e32 v181, v66
	v_exp_f32_e32 v66, v50
	v_mov_b32_e32 v50, v181
	s_waitcnt lgkmcnt(0)
	v_add_f32_e32 v67, v67, v154
	v_add_f32_e32 v51, v51, v155
	v_exp_f32_e32 v181, v67
	v_exp_f32_e32 v67, v51
	v_mov_b32_e32 v51, v181
	ds_read_b32 v156, v182 offset:32
	ds_read_b32 v157, v182 offset:160
	ds_read_b32 v158, v182 offset:36
	ds_read_b32 v159, v182 offset:164
	ds_read_b32 v160, v182 offset:40
	ds_read_b32 v161, v182 offset:168
	ds_read_b32 v162, v182 offset:44
	ds_read_b32 v163, v182 offset:172
	s_waitcnt lgkmcnt(6)
	v_add_f32_e32 v68, v68, v156
	v_add_f32_e32 v52, v52, v157
	v_exp_f32_e32 v181, v68
	v_exp_f32_e32 v68, v52
	v_mov_b32_e32 v52, v181
	s_waitcnt lgkmcnt(4)
	v_add_f32_e32 v69, v69, v158
	v_add_f32_e32 v53, v53, v159
	v_exp_f32_e32 v181, v69
	v_exp_f32_e32 v69, v53
	v_mov_b32_e32 v53, v181
	s_waitcnt lgkmcnt(2)
	v_add_f32_e32 v70, v70, v160
	v_add_f32_e32 v54, v54, v161
	v_exp_f32_e32 v181, v70
	v_exp_f32_e32 v70, v54
	v_mov_b32_e32 v54, v181
	s_waitcnt lgkmcnt(0)
	v_add_f32_e32 v71, v71, v162
	v_add_f32_e32 v55, v55, v163
	v_exp_f32_e32 v181, v71
	v_exp_f32_e32 v71, v55
	v_mov_b32_e32 v55, v181
	ds_read_b32 v164, v182 offset:64
	ds_read_b32 v165, v182 offset:192
	ds_read_b32 v166, v182 offset:68
	ds_read_b32 v167, v182 offset:196
	ds_read_b32 v168, v182 offset:72
	ds_read_b32 v169, v182 offset:200
	ds_read_b32 v170, v182 offset:76
	ds_read_b32 v171, v182 offset:204
	s_waitcnt lgkmcnt(6)
	v_add_f32_e32 v72, v72, v164
	v_add_f32_e32 v56, v56, v165
	v_exp_f32_e32 v181, v72
	v_exp_f32_e32 v72, v56
	v_mov_b32_e32 v56, v181
	s_waitcnt lgkmcnt(4)
	v_add_f32_e32 v73, v73, v166
	v_add_f32_e32 v57, v57, v167
	v_exp_f32_e32 v181, v73
	v_exp_f32_e32 v73, v57
	v_mov_b32_e32 v57, v181
	s_waitcnt lgkmcnt(2)
	v_add_f32_e32 v74, v74, v168
	v_add_f32_e32 v58, v58, v169
	v_exp_f32_e32 v181, v74
	v_exp_f32_e32 v74, v58
	v_mov_b32_e32 v58, v181
	s_waitcnt lgkmcnt(0)
	v_add_f32_e32 v75, v75, v170
	v_add_f32_e32 v59, v59, v171
	v_exp_f32_e32 v181, v75
	v_exp_f32_e32 v75, v59
	v_mov_b32_e32 v59, v181
	ds_read_b32 v172, v182 offset:96
	ds_read_b32 v173, v182 offset:224
	ds_read_b32 v174, v182 offset:100
	ds_read_b32 v175, v182 offset:228
	ds_read_b32 v176, v182 offset:104
	ds_read_b32 v177, v182 offset:232
	ds_read_b32 v178, v182 offset:108
	ds_read_b32 v179, v182 offset:236
	s_waitcnt lgkmcnt(6)
	v_add_f32_e32 v76, v76, v172
	v_add_f32_e32 v60, v60, v173
	v_exp_f32_e32 v181, v76
	v_exp_f32_e32 v76, v60
	v_mov_b32_e32 v60, v181
	s_waitcnt lgkmcnt(4)
	v_add_f32_e32 v77, v77, v174
	v_add_f32_e32 v61, v61, v175
	v_exp_f32_e32 v181, v77
	v_exp_f32_e32 v77, v61
	v_mov_b32_e32 v61, v181
	s_waitcnt lgkmcnt(2)
	v_add_f32_e32 v78, v78, v176
	v_add_f32_e32 v62, v62, v177
	v_exp_f32_e32 v181, v78
	v_exp_f32_e32 v78, v62
	v_mov_b32_e32 v62, v181
	s_waitcnt lgkmcnt(0)
	v_add_f32_e32 v79, v79, v178
	v_add_f32_e32 v63, v63, v179
	v_exp_f32_e32 v181, v79
	v_exp_f32_e32 v79, v63
	v_mov_b32_e32 v63, v181
; __device__ void attn_b_item(const Params& p, int item, int l, unsigned char* smem) {
;     ...
; #pragma unroll
;         for (int i = 0; i < 4; ++i) { la4 += (f32x4){p0[4 * i], p0[4 * i + 1], p0[4 * i + 2], p0[4 * i + 3]}; la4 += (f32x4){p1[4 * i], p1[4 * i + 1], p1[4 * i + 2], p1[4 * i + 3]}; }
;         at_pv2(o0, o1, p0, p1, vf0, vf1);
;     }
;     float lacc = (la4.x + la4.y) + (la4.z + la4.w);
;     lacc += __shfl_xor(lacc, 32);
;     if (hi == 0) { lq[r32] = lacc; LSE[(size_t)qpos * 4] = (-nshift + log2f(lacc)) * LN2; }
.Latb_join:
	v_pk_add_f32 v[132:133], v[132:133], v[48:49]
	v_cvt_pk_bf16_f32 v48, v48, v49
	v_pk_add_f32 v[132:133], v[64:65], v[132:133]
	v_cvt_pk_bf16_f32 v64, v64, v65
	v_pk_add_f32 v[134:135], v[134:135], v[50:51]
	v_cvt_pk_bf16_f32 v65, v66, v67
	v_pk_add_f32 v[134:135], v[66:67], v[134:135]
	v_cvt_pk_bf16_f32 v49, v50, v51
	v_pk_add_f32 v[132:133], v[132:133], v[52:53]
	v_cvt_pk_bf16_f32 v66, v68, v69
	v_pk_add_f32 v[132:133], v[68:69], v[132:133]
	v_cvt_pk_bf16_f32 v50, v52, v53
	v_pk_add_f32 v[134:135], v[134:135], v[54:55]
	v_cvt_pk_bf16_f32 v67, v70, v71
	v_pk_add_f32 v[134:135], v[70:71], v[134:135]
	v_cvt_pk_bf16_f32 v51, v54, v55
	v_pk_add_f32 v[132:133], v[132:133], v[56:57]
	v_cvt_pk_bf16_f32 v56, v56, v57
	v_pk_add_f32 v[132:133], v[72:73], v[132:133]
	v_cvt_pk_bf16_f32 v72, v72, v73
	v_pk_add_f32 v[134:135], v[134:135], v[58:59]
	v_cvt_pk_bf16_f32 v73, v74, v75
	v_pk_add_f32 v[134:135], v[74:75], v[134:135]
	v_cvt_pk_bf16_f32 v57, v58, v59
	v_pk_add_f32 v[132:133], v[132:133], v[60:61]
	v_cvt_pk_bf16_f32 v74, v76, v77
	v_pk_add_f32 v[132:133], v[76:77], v[132:133]
	v_cvt_pk_bf16_f32 v58, v60, v61
	v_pk_add_f32 v[134:135], v[134:135], v[62:63]
	v_pk_add_f32 v[134:135], v[78:79], v[134:135]
	v_cvt_pk_bf16_f32 v75, v78, v79
	v_cvt_pk_bf16_f32 v59, v62, v63
	s_setprio 1
	v_mfma_f32_32x32x16_bf16 v[0:15], v[48:51], v[122:125], v[0:15]
	v_mfma_f32_32x32x16_bf16 v[16:31], v[48:51], v[126:129], v[16:31]
	v_mfma_f32_32x32x16_bf16 v[0:15], v[56:59], v[110:113], v[0:15]
	v_mfma_f32_32x32x16_bf16 v[16:31], v[56:59], v[118:121], v[16:31]
	v_mfma_f32_32x32x16_bf16 v[0:15], v[64:67], v[106:109], v[0:15]
	v_mfma_f32_32x32x16_bf16 v[16:31], v[64:67], v[114:117], v[16:31]
	v_mfma_f32_32x32x16_bf16 v[0:15], v[72:75], v[98:101], v[0:15]
	v_mfma_f32_32x32x16_bf16 v[16:31], v[72:75], v[102:105], v[16:31]
	s_setprio 0
	s_add_i32 s62, s62, 64
	v_add_u32_e32 v142, 0x4400, v142
	s_cmpk_eq_i32 s62, 0xc0
	v_add_u32_e32 v80, 0x4400, v80
	s_cbranch_scc0 .LBB0_787
	v_add_f32_e32 v32, v132, v133
	v_add_f32_e32 v33, v134, v135
	v_cmp_lt_i32_e32 vcc, v223, v217
	v_add_f32_e32 v32, v32, v33
	s_lshl_b32 s9, s58, 2
	v_cndmask_b32_e32 v33, v216, v223, vcc
	v_lshlrev_b32_e32 v33, 2, v33
	ds_bpermute_b32 v33, v33, v32
	s_add_i32 s9, s9, 0
	s_add_i32 s9, s9, 0x19800
	v_cmp_gt_u32_e32 vcc, 32, v139
	s_and_saveexec_b64 s[36:37], vcc
	s_cbranch_execz .LBB0_781
	s_waitcnt lgkmcnt(0)
	v_add_f32_e32 v32, v32, v33
	v_cmp_gt_f32_e32 vcc, s35, v32
	s_lshl_b64 s[16:17], s[42:43], 17
	v_lshl_add_u32 v34, v137, 2, s9
	v_cndmask_b32_e64 v33, 0, 32, vcc
	v_ldexp_f32 v33, v32, v33
	v_log_f32_e32 v33, v33
	s_add_u32 s16, s50, s16
	ds_write_b32 v34, v32
	v_mov_b32_e32 v32, 0x42000000
	s_addc_u32 s17, s51, s17
	s_lshl_b32 s18, s54, 2
	v_cndmask_b32_e32 v32, 0, v32, vcc
	s_add_u32 s16, s16, s18
	v_sub_f32_e32 v32, v33, v32
	s_addc_u32 s17, s17, 0
	v_add_f32_e32 v32, v138, v32
	v_mul_f32_e32 v34, 0x3f317218, v32
	v_lshl_add_u64 v[32:33], v[130:131], 4, s[16:17]
	global_store_dword v[32:33], v34, off
	s_branch .LBB0_781
